# prompt attention P.V cluster (no-mask path): counted lgkmcnt waits per MFMA instead of lgkmcnt(0) per group of four, plus partialSM between the MFMAs
# speedup vs baseline: 1.0076x; 1.0076x over previous
.LBB0_1167:
	ds_read_b128 v[80:83], v189
	ds_read_b128 v[84:87], v189 offset:32
	ds_read_b128 v[64:67], v189 offset:128
	ds_read_b128 v[68:71], v189 offset:160
	ds_read_b128 v[88:91], v189 offset:64
	ds_read_b128 v[72:75], v189 offset:192
	ds_read_b128 v[92:95], v189 offset:96
	ds_read_b128 v[76:79], v189 offset:224
	ds_read_b128 v[206:209], v181 offset:49152
	ds_read_b128 v[210:213], v181 offset:57344
	v_add_f32_e32 v146, 0, v147
	v_add_f32_e32 v146, v148, v146
	v_add_f32_e32 v146, v149, v146
	s_waitcnt lgkmcnt(1)
	v_mfma_f32_32x32x16_bf16 v[80:95], v[206:209], v[126:129], v[80:95]
	v_add_f32_e32 v146, v202, v146
	v_add_f32_e32 v146, v203, v146
	v_add_f32_e32 v146, v205, v146
	v_add_f32_e32 v146, v201, v146
	v_add_f32_e32 v146, v204, v146
	v_add_f32_e32 v146, v193, v146
	v_add_f32_e32 v146, v195, v146
	s_waitcnt lgkmcnt(0)
	v_mfma_f32_32x32x16_bf16 v[64:79], v[210:213], v[126:129], v[64:79]
	ds_read_b128 v[206:209], v182 offset:49152
	ds_read_b128 v[210:213], v182 offset:57344
	v_add_f32_e32 v146, v196, v146
	v_add_f32_e32 v146, v199, v146
	v_exp_f32_e32 v142, v142
	v_add_f32_e32 v146, v194, v146
	v_exp_f32_e32 v143, v143
	v_add_f32_e32 v146, v197, v146
	s_waitcnt lgkmcnt(1)
	v_mfma_f32_32x32x16_bf16 v[80:95], v[206:209], v[122:125], v[80:95]
	v_exp_f32_e32 v140, v140
	v_add_f32_e32 v146, v198, v146
	v_exp_f32_e32 v141, v141
	v_add_f32_e32 v146, v200, v146
	v_exp_f32_e32 v136, v136
	v_add_f32_e32 v146, v142, v146
	v_exp_f32_e32 v137, v137
	s_waitcnt lgkmcnt(0)
	v_mfma_f32_32x32x16_bf16 v[64:79], v[210:213], v[122:125], v[64:79]
	ds_read_b128 v[206:209], v180 offset:49152
	ds_read_b128 v[210:213], v180 offset:57344
	v_add_f32_e32 v146, v143, v146
	v_exp_f32_e32 v134, v134
	v_add_f32_e32 v146, v140, v146
	v_exp_f32_e32 v135, v135
	v_add_f32_e32 v146, v141, v146
	v_exp_f32_e32 v130, v130
	s_waitcnt lgkmcnt(1)
	v_mfma_f32_32x32x16_bf16 v[80:95], v[206:209], v[118:121], v[80:95]
	v_add_f32_e32 v146, v136, v146
	v_exp_f32_e32 v131, v131
	v_add_f32_e32 v146, v137, v146
	v_exp_f32_e32 v144, v144
	v_add_f32_e32 v146, v134, v146
	v_exp_f32_e32 v145, v145
	v_add_f32_e32 v146, v135, v146
	s_waitcnt lgkmcnt(0)
	v_mfma_f32_32x32x16_bf16 v[64:79], v[210:213], v[118:121], v[64:79]
	ds_read_b128 v[206:209], v151 offset:49152
	ds_read_b128 v[210:213], v151 offset:57344
	v_exp_f32_e32 v138, v138
	v_add_f32_e32 v146, v130, v146
	v_exp_f32_e32 v139, v139
	v_add_f32_e32 v146, v131, v146
	v_exp_f32_e32 v132, v132
	v_add_f32_e32 v146, v144, v146
	s_waitcnt lgkmcnt(1)
	v_mfma_f32_32x32x16_bf16 v[80:95], v[206:209], v[114:117], v[80:95]
	v_exp_f32_e32 v133, v133
	v_add_f32_e32 v146, v145, v146
	v_add_f32_e32 v146, v138, v146
	v_add_f32_e32 v146, v139, v146
	v_add_f32_e32 v146, v132, v146
	v_add_f32_e32 v190, v133, v146
	v_mov_b32_e32 v191, v190
	s_waitcnt lgkmcnt(0)
	v_mfma_f32_32x32x16_bf16 v[64:79], v[210:213], v[114:117], v[64:79]
	ds_read_b128 v[206:209], v181 offset:49280
	ds_read_b128 v[210:213], v181 offset:57472
	v_permlane32_swap_b32_e32 v190, v191
	v_cvt_pk_bf16_f32 v146, v147, v148
	v_cvt_pk_bf16_f32 v147, v149, v202
	v_cvt_pk_bf16_f32 v148, v203, v205
	v_cvt_pk_bf16_f32 v149, v201, v204
	s_waitcnt lgkmcnt(1)
	v_mfma_f32_32x32x16_bf16 v[80:95], v[206:209], v[110:113], v[80:95]
	v_cvt_pk_bf16_f32 v192, v193, v195
	v_cvt_pk_bf16_f32 v193, v196, v199
	v_cvt_pk_bf16_f32 v194, v194, v197
	v_cvt_pk_bf16_f32 v195, v198, v200
	v_cvt_pk_bf16_f32 v196, v142, v143
	v_cvt_pk_bf16_f32 v197, v140, v141
	v_cvt_pk_bf16_f32 v198, v136, v137
	s_waitcnt lgkmcnt(0)
	v_mfma_f32_32x32x16_bf16 v[64:79], v[210:213], v[110:113], v[64:79]
	ds_read_b128 v[206:209], v182 offset:49280
	ds_read_b128 v[210:213], v182 offset:57472
	v_cvt_pk_bf16_f32 v199, v134, v135
	v_cvt_pk_bf16_f32 v200, v130, v131
	v_cvt_pk_bf16_f32 v201, v144, v145
	v_cvt_pk_bf16_f32 v202, v138, v139
	v_cvt_pk_bf16_f32 v203, v132, v133
	v_permlane32_swap_b32_e32 v146, v148
	s_waitcnt lgkmcnt(1)
	v_mfma_f32_32x32x16_bf16 v[80:95], v[206:209], v[106:109], v[80:95]
	v_permlane32_swap_b32_e32 v147, v149
	v_permlane32_swap_b32_e32 v192, v194
	v_permlane32_swap_b32_e32 v193, v195
	v_permlane32_swap_b32_e32 v196, v198
	s_waitcnt lgkmcnt(0)
	v_mfma_f32_32x32x16_bf16 v[64:79], v[210:213], v[106:109], v[64:79]
	ds_read_b128 v[206:209], v180 offset:49280
	ds_read_b128 v[210:213], v180 offset:57472
	v_permlane32_swap_b32_e32 v197, v199
	v_permlane32_swap_b32_e32 v200, v202
	v_permlane32_swap_b32_e32 v201, v203
	s_waitcnt lgkmcnt(1)
	v_mfma_f32_32x32x16_bf16 v[80:95], v[206:209], v[102:105], v[80:95]
	s_waitcnt lgkmcnt(0)
	v_mfma_f32_32x32x16_bf16 v[64:79], v[210:213], v[102:105], v[64:79]
	ds_read_b128 v[206:209], v151 offset:49280
	ds_read_b128 v[210:213], v151 offset:57472
	s_waitcnt lgkmcnt(1)
	v_mfma_f32_32x32x16_bf16 v[80:95], v[206:209], v[98:101], v[80:95]
	s_waitcnt lgkmcnt(0)
	v_mfma_f32_32x32x16_bf16 v[64:79], v[210:213], v[98:101], v[64:79]
	v_lshl_add_u64 v[130:131], v[156:157], 0, v[96:97]
	v_lshl_add_u64 v[134:135], v[152:153], 0, v[96:97]
	v_lshl_add_u64 v[138:139], v[158:159], 0, v[96:97]
	v_lshl_add_u64 v[142:143], v[154:155], 0, v[96:97]
	global_load_dwordx4 v[130:133], v[130:131], off
	s_nop 0
	global_load_dwordx4 v[134:137], v[134:135], off
	s_nop 0
	global_load_dwordx4 v[138:141], v[138:139], off
	s_nop 0
	global_load_dwordx4 v[142:145], v[142:143], off
	s_sub_i32 s6, s92, 64
	s_cmp_le_i32 s6, s41
	s_cbranch_scc0 .Lpvm_1167a
	ds_read_b64_tr_b16 v[204:205], v174 offset:0
	ds_read_b64_tr_b16 v[206:207], v174 offset:0x800
	ds_read_b64_tr_b16 v[208:209], v174 offset:0x1000
	ds_read_b64_tr_b16 v[210:211], v174 offset:0x1800
	ds_read_b64_tr_b16 v[220:221], v174 offset:0x2000
	ds_read_b64_tr_b16 v[222:223], v174 offset:0x2800
	ds_read_b64_tr_b16 v[224:225], v174 offset:0x3000
	ds_read_b64_tr_b16 v[226:227], v174 offset:0x3800
	s_nop 0
	s_waitcnt lgkmcnt(6)
	v_mfma_f32_32x32x16_bf16 v[48:63], v[146:149], v[204:207], v[48:63]
	v_max_f32_e32 v230, v81, v81
	v_max_f32_e32 v231, v80, v80
	v_max_f32_e32 v230, v231, v230
	ds_read_b64_tr_b16 v[204:205], v174 offset:0x200
	ds_read_b64_tr_b16 v[206:207], v174 offset:0xa00
	s_waitcnt lgkmcnt(6)
	v_mfma_f32_32x32x16_bf16 v[48:63], v[192:195], v[208:211], v[48:63]
	v_max3_f32 v230, v230, v82, v83
	v_max3_f32 v230, v230, v84, v85
	v_max3_f32 v230, v230, v86, v87
	ds_read_b64_tr_b16 v[208:209], v174 offset:0x1200
	ds_read_b64_tr_b16 v[210:211], v174 offset:0x1a00
	s_waitcnt lgkmcnt(6)
	v_mfma_f32_32x32x16_bf16 v[48:63], v[196:199], v[220:223], v[48:63]
	v_max3_f32 v230, v230, v88, v89
	v_max3_f32 v230, v230, v90, v91
	v_max3_f32 v230, v230, v92, v93
	ds_read_b64_tr_b16 v[220:221], v174 offset:0x2200
	ds_read_b64_tr_b16 v[222:223], v174 offset:0x2a00
	s_waitcnt lgkmcnt(6)
	v_mfma_f32_32x32x16_bf16 v[48:63], v[200:203], v[224:227], v[48:63]
	v_max3_f32 v230, v230, v94, v95
	v_max3_f32 v230, v230, v64, v65
	v_max3_f32 v230, v230, v66, v67
	ds_read_b64_tr_b16 v[224:225], v174 offset:0x3200
	ds_read_b64_tr_b16 v[226:227], v174 offset:0x3a00
	s_waitcnt lgkmcnt(6)
	v_mfma_f32_32x32x16_bf16 v[32:47], v[146:149], v[204:207], v[32:47]
	v_max3_f32 v230, v230, v68, v69
	v_max3_f32 v230, v230, v70, v71
	v_max3_f32 v230, v230, v72, v73
	ds_read_b64_tr_b16 v[204:205], v174 offset:0x400
	ds_read_b64_tr_b16 v[206:207], v174 offset:0xc00
	s_waitcnt lgkmcnt(6)
	v_mfma_f32_32x32x16_bf16 v[32:47], v[192:195], v[208:211], v[32:47]
	v_max3_f32 v230, v230, v74, v75
	v_max3_f32 v230, v230, v76, v77
	v_max3_f32 v230, v230, v78, v79
	ds_read_b64_tr_b16 v[208:209], v174 offset:0x1400
	ds_read_b64_tr_b16 v[210:211], v174 offset:0x1c00
	s_waitcnt lgkmcnt(6)
	v_mfma_f32_32x32x16_bf16 v[32:47], v[196:199], v[220:223], v[32:47]
	v_mov_b32_e32 v231, v230
	s_nop 1
	v_permlane32_swap_b32_e32 v230, v231
	ds_read_b64_tr_b16 v[220:221], v174 offset:0x2400
	ds_read_b64_tr_b16 v[222:223], v174 offset:0x2c00
	s_waitcnt lgkmcnt(6)
	v_mfma_f32_32x32x16_bf16 v[32:47], v[200:203], v[224:227], v[32:47]
	v_max_f32_e32 v231, v231, v231
	v_max_f32_e32 v230, v230, v230
	v_max_f32_e32 v230, v230, v231
	ds_read_b64_tr_b16 v[224:225], v174 offset:0x3400
	ds_read_b64_tr_b16 v[226:227], v174 offset:0x3c00
	s_waitcnt lgkmcnt(6)
	v_mfma_f32_32x32x16_bf16 v[16:31], v[146:149], v[204:207], v[16:31]
	v_sub_f32_e32 v231, v230, v187
	v_mul_f32_e32 v231, 0x3db504f3, v231
	s_mov_b32 s6, 0x41000000
	ds_read_b64_tr_b16 v[204:205], v174 offset:0x600
	ds_read_b64_tr_b16 v[206:207], v174 offset:0xe00
	s_waitcnt lgkmcnt(6)
	v_mfma_f32_32x32x16_bf16 v[16:31], v[192:195], v[208:211], v[16:31]
	v_cmp_ge_f32_e32 vcc, s6, v231
	v_max_f32_e32 v231, v187, v187
	v_max_f32_e32 v230, v231, v230
	ds_read_b64_tr_b16 v[208:209], v174 offset:0x1600
	ds_read_b64_tr_b16 v[210:211], v174 offset:0x1e00
	s_waitcnt lgkmcnt(6)
	v_mfma_f32_32x32x16_bf16 v[16:31], v[196:199], v[220:223], v[16:31]
	v_sub_f32_e32 v231, v187, v230
	v_mul_f32_e32 v231, 0x3e0293ee, v231
	v_exp_f32_e32 v231, v231
	ds_read_b64_tr_b16 v[220:221], v174 offset:0x2600
	ds_read_b64_tr_b16 v[222:223], v174 offset:0x2e00
	s_waitcnt lgkmcnt(6)
	v_mfma_f32_32x32x16_bf16 v[16:31], v[200:203], v[224:227], v[16:31]
	ds_read_b64_tr_b16 v[224:225], v174 offset:0x3600
	ds_read_b64_tr_b16 v[226:227], v174 offset:0x3e00
	s_waitcnt lgkmcnt(6)
	v_mfma_f32_32x32x16_bf16 v[0:15], v[146:149], v[204:207], v[0:15]
	s_waitcnt lgkmcnt(4)
	v_mfma_f32_32x32x16_bf16 v[0:15], v[192:195], v[208:211], v[0:15]
	s_waitcnt lgkmcnt(2)
	v_mfma_f32_32x32x16_bf16 v[0:15], v[196:199], v[220:223], v[0:15]
	s_waitcnt lgkmcnt(0)
	v_mfma_f32_32x32x16_bf16 v[0:15], v[200:203], v[224:227], v[0:15]
	s_nop 0
	v_mov_b32_e32 v146, v230
	v_mov_b32_e32 v147, v231
	s_branch .Lpvj_1167a

.LBB0_1173:
	v_cndmask_b32_e64 v187, v146, v187, s[6:7]
	v_mul_f32_e32 v146, 0xbe0293ee, v187
	v_fmamk_f32 v80, v80, 0x3e0293ee, v146
	v_fmamk_f32 v81, v81, 0x3e0293ee, v146
	v_fmamk_f32 v82, v82, 0x3e0293ee, v146
	v_fmamk_f32 v83, v83, 0x3e0293ee, v146
	v_fmamk_f32 v84, v84, 0x3e0293ee, v146
	v_fmamk_f32 v85, v85, 0x3e0293ee, v146
	v_fmamk_f32 v86, v86, 0x3e0293ee, v146
	v_fmamk_f32 v87, v87, 0x3e0293ee, v146
	v_fmamk_f32 v88, v88, 0x3e0293ee, v146
	v_fmamk_f32 v89, v89, 0x3e0293ee, v146
	v_fmamk_f32 v90, v90, 0x3e0293ee, v146
	v_fmamk_f32 v91, v91, 0x3e0293ee, v146
	v_fmamk_f32 v92, v92, 0x3e0293ee, v146
	v_fmamk_f32 v93, v93, 0x3e0293ee, v146
	v_fmamk_f32 v94, v94, 0x3e0293ee, v146
	v_fmamk_f32 v95, v95, 0x3e0293ee, v146
	v_exp_f32_e32 v139, v80
	v_exp_f32_e32 v141, v81
	v_exp_f32_e32 v142, v82
	v_exp_f32_e32 v143, v83
	v_exp_f32_e32 v144, v84
	v_exp_f32_e32 v145, v85
	v_exp_f32_e32 v138, v86
	v_exp_f32_e32 v140, v87
	v_exp_f32_e32 v133, v88
	v_exp_f32_e32 v135, v89
	v_exp_f32_e32 v136, v90
	v_exp_f32_e32 v137, v91
	v_exp_f32_e32 v130, v92
	v_exp_f32_e32 v131, v93
	v_exp_f32_e32 v132, v94
	v_exp_f32_e32 v134, v95
	v_fmamk_f32 v198, v64, 0x3e0293ee, v146
	v_fmamk_f32 v199, v65, 0x3e0293ee, v146
	v_fmamk_f32 v200, v66, 0x3e0293ee, v146
	v_fmamk_f32 v201, v67, 0x3e0293ee, v146
	v_fmamk_f32 v202, v68, 0x3e0293ee, v146
	v_fmamk_f32 v148, v69, 0x3e0293ee, v146
	v_fmamk_f32 v149, v70, 0x3e0293ee, v146
	v_fmamk_f32 v193, v71, 0x3e0293ee, v146
	v_fmamk_f32 v194, v72, 0x3e0293ee, v146
	v_fmamk_f32 v195, v73, 0x3e0293ee, v146
	v_fmamk_f32 v196, v74, 0x3e0293ee, v146
	v_fmamk_f32 v197, v75, 0x3e0293ee, v146
	v_fmamk_f32 v147, v76, 0x3e0293ee, v146
	v_fmamk_f32 v203, v77, 0x3e0293ee, v146
	v_fmamk_f32 v204, v78, 0x3e0293ee, v146
	v_fmac_f32_e32 v146, 0x3e0293ee, v79
	s_waitcnt lgkmcnt(0)
	s_barrier
	ds_read_b128 v[80:83], v189 offset:256
	ds_read_b128 v[84:87], v189 offset:288
	ds_read_b128 v[64:67], v189 offset:384
	ds_read_b128 v[68:71], v189 offset:416
	ds_read_b128 v[88:91], v189 offset:320
	ds_read_b128 v[72:75], v189 offset:448
	ds_read_b128 v[92:95], v189 offset:352
	ds_read_b128 v[76:79], v189 offset:480
	ds_read_b128 v[206:209], v181 offset:32768
	ds_read_b128 v[210:213], v181 offset:40960
	v_exp_f32_e32 v218, v146
	v_add_f32_e32 v146, 0, v139
	v_add_f32_e32 v146, v141, v146
	s_waitcnt lgkmcnt(1)
	v_mfma_f32_32x32x16_bf16 v[80:95], v[206:209], v[126:129], v[80:95]
	v_add_f32_e32 v146, v142, v146
	v_add_f32_e32 v146, v143, v146
	v_add_f32_e32 v146, v144, v146
	v_add_f32_e32 v146, v145, v146
	v_add_f32_e32 v146, v138, v146
	v_add_f32_e32 v146, v140, v146
	v_add_f32_e32 v146, v133, v146
	s_waitcnt lgkmcnt(0)
	v_mfma_f32_32x32x16_bf16 v[64:79], v[210:213], v[126:129], v[64:79]
	ds_read_b128 v[206:209], v182 offset:32768
	ds_read_b128 v[210:213], v182 offset:40960
	v_add_f32_e32 v146, v135, v146
	v_add_f32_e32 v146, v136, v146
	v_add_f32_e32 v146, v137, v146
	v_exp_f32_e32 v198, v198
	v_add_f32_e32 v146, v130, v146
	v_exp_f32_e32 v199, v199
	s_waitcnt lgkmcnt(1)
	v_mfma_f32_32x32x16_bf16 v[80:95], v[206:209], v[122:125], v[80:95]
	v_add_f32_e32 v146, v131, v146
	v_exp_f32_e32 v200, v200
	v_add_f32_e32 v146, v132, v146
	v_exp_f32_e32 v201, v201
	v_add_f32_e32 v146, v134, v146
	v_exp_f32_e32 v202, v202
	v_add_f32_e32 v146, v198, v146
	s_waitcnt lgkmcnt(0)
	v_mfma_f32_32x32x16_bf16 v[64:79], v[210:213], v[122:125], v[64:79]
	ds_read_b128 v[206:209], v180 offset:32768
	ds_read_b128 v[210:213], v180 offset:40960
	v_exp_f32_e32 v205, v148
	v_add_f32_e32 v146, v199, v146
	v_add_f32_e32 v146, v200, v146
	v_exp_f32_e32 v193, v193
	v_add_f32_e32 v146, v201, v146
	v_add_f32_e32 v146, v202, v146
	s_waitcnt lgkmcnt(1)
	v_mfma_f32_32x32x16_bf16 v[80:95], v[206:209], v[118:121], v[80:95]
	v_add_f32_e32 v146, v205, v146
	v_exp_f32_e32 v214, v203
	v_exp_f32_e32 v215, v204
	v_cvt_pk_bf16_f32 v148, v144, v145
	v_cvt_pk_bf16_f32 v198, v198, v199
	v_cvt_pk_bf16_f32 v199, v200, v201
	v_cvt_pk_bf16_f32 v200, v202, v205
	s_waitcnt lgkmcnt(0)
	v_mfma_f32_32x32x16_bf16 v[64:79], v[210:213], v[118:121], v[64:79]
	ds_read_b128 v[206:209], v151 offset:32768
	ds_read_b128 v[210:213], v151 offset:40960
	v_cvt_pk_bf16_f32 v205, v215, v218
	v_permlane32_swap_b32_e32 v198, v200
	s_waitcnt lgkmcnt(1)
	v_mfma_f32_32x32x16_bf16 v[80:95], v[206:209], v[114:117], v[80:95]
	s_waitcnt lgkmcnt(0)
	v_mfma_f32_32x32x16_bf16 v[64:79], v[210:213], v[114:117], v[64:79]
	ds_read_b128 v[206:209], v181 offset:32896
	ds_read_b128 v[210:213], v181 offset:41088
	s_waitcnt lgkmcnt(1)
	v_mfma_f32_32x32x16_bf16 v[80:95], v[206:209], v[110:113], v[80:95]
	s_waitcnt lgkmcnt(0)
	v_mfma_f32_32x32x16_bf16 v[64:79], v[210:213], v[110:113], v[64:79]
	ds_read_b128 v[206:209], v182 offset:32896
	ds_read_b128 v[210:213], v182 offset:41088
	s_waitcnt lgkmcnt(1)
	v_mfma_f32_32x32x16_bf16 v[80:95], v[206:209], v[106:109], v[80:95]
	s_waitcnt lgkmcnt(0)
	v_mfma_f32_32x32x16_bf16 v[64:79], v[210:213], v[106:109], v[64:79]
	ds_read_b128 v[206:209], v180 offset:32896
	ds_read_b128 v[210:213], v180 offset:41088
	s_waitcnt lgkmcnt(1)
	v_mfma_f32_32x32x16_bf16 v[80:95], v[206:209], v[102:105], v[80:95]
	s_waitcnt lgkmcnt(0)
	v_mfma_f32_32x32x16_bf16 v[64:79], v[210:213], v[102:105], v[64:79]
	ds_read_b128 v[206:209], v151 offset:32896
	ds_read_b128 v[210:213], v151 offset:41088
	s_waitcnt lgkmcnt(1)
	v_mfma_f32_32x32x16_bf16 v[80:95], v[206:209], v[98:101], v[80:95]
	v_exp_f32_e32 v208, v149
	v_exp_f32_e32 v209, v194
	v_cvt_pk_bf16_f32 v149, v138, v140
	v_cvt_pk_bf16_f32 v194, v133, v135
	v_add_f32_e32 v146, v208, v146
	v_add_f32_e32 v146, v193, v146
	v_add_f32_e32 v146, v209, v146
	s_waitcnt lgkmcnt(0)
	v_mfma_f32_32x32x16_bf16 v[64:79], v[210:213], v[98:101], v[64:79]
	v_exp_f32_e32 v210, v195
	v_exp_f32_e32 v211, v196
	v_exp_f32_e32 v212, v197
	v_exp_f32_e32 v213, v147
	v_add_f32_e32 v146, v210, v146
	v_add_f32_e32 v146, v211, v146
	v_add_f32_e32 v146, v212, v146
	v_add_f32_e32 v146, v213, v146
	v_add_f32_e32 v146, v214, v146
	v_add_f32_e32 v146, v215, v146
	v_add_f32_e32 v206, v218, v146
	v_mov_b32_e32 v207, v206
	s_nop 1
	v_permlane32_swap_b32_e32 v206, v207
	v_cvt_pk_bf16_f32 v146, v139, v141
	v_cvt_pk_bf16_f32 v147, v142, v143
	v_cvt_pk_bf16_f32 v195, v136, v137
	v_cvt_pk_bf16_f32 v196, v130, v131
	v_cvt_pk_bf16_f32 v197, v132, v134
	v_cvt_pk_bf16_f32 v201, v208, v193
	v_cvt_pk_bf16_f32 v202, v209, v210
	v_cvt_pk_bf16_f32 v203, v211, v212
	v_cvt_pk_bf16_f32 v204, v213, v214
	v_permlane32_swap_b32_e32 v146, v148
	v_permlane32_swap_b32_e32 v147, v149
	v_permlane32_swap_b32_e32 v194, v196
	v_permlane32_swap_b32_e32 v195, v197
	v_permlane32_swap_b32_e32 v199, v201
	v_permlane32_swap_b32_e32 v202, v204
	v_permlane32_swap_b32_e32 v203, v205
	v_lshl_add_u64 v[130:131], v[164:165], 0, v[96:97]
	v_lshl_add_u64 v[134:135], v[160:161], 0, v[96:97]
	v_lshl_add_u64 v[138:139], v[166:167], 0, v[96:97]
	v_lshl_add_u64 v[142:143], v[162:163], 0, v[96:97]
	global_load_dwordx4 v[130:133], v[130:131], off
	s_nop 0
	global_load_dwordx4 v[134:137], v[134:135], off
	s_nop 0
	global_load_dwordx4 v[138:141], v[138:139], off
	s_nop 0
	global_load_dwordx4 v[142:145], v[142:143], off
	s_cmp_le_i32 s92, s41
	s_cbranch_scc0 .Lpvm_1167b
	ds_read_b64_tr_b16 v[208:209], v174 offset:0x4000
	ds_read_b64_tr_b16 v[210:211], v174 offset:0x4800
	ds_read_b64_tr_b16 v[220:221], v174 offset:0x5000
	ds_read_b64_tr_b16 v[222:223], v174 offset:0x5800
	ds_read_b64_tr_b16 v[224:225], v174 offset:0x6000
	ds_read_b64_tr_b16 v[226:227], v174 offset:0x6800
	ds_read_b64_tr_b16 v[238:239], v174 offset:0x7000
	ds_read_b64_tr_b16 v[240:241], v174 offset:0x7800
	s_nop 0
	s_waitcnt lgkmcnt(6)
	v_mfma_f32_32x32x16_bf16 v[48:63], v[146:149], v[208:211], v[48:63]
	v_max_f32_e32 v230, v81, v81
	v_max_f32_e32 v231, v80, v80
	v_max_f32_e32 v230, v231, v230
	ds_read_b64_tr_b16 v[208:209], v174 offset:0x4200
	ds_read_b64_tr_b16 v[210:211], v174 offset:0x4a00
	s_waitcnt lgkmcnt(6)
	v_mfma_f32_32x32x16_bf16 v[48:63], v[194:197], v[220:223], v[48:63]
	v_max3_f32 v230, v230, v82, v83
	v_max3_f32 v230, v230, v84, v85
	v_max3_f32 v230, v230, v86, v87
	ds_read_b64_tr_b16 v[220:221], v174 offset:0x5200
	ds_read_b64_tr_b16 v[222:223], v174 offset:0x5a00
	s_waitcnt lgkmcnt(6)
	v_mfma_f32_32x32x16_bf16 v[48:63], v[198:201], v[224:227], v[48:63]
	v_max3_f32 v230, v230, v88, v89
	v_max3_f32 v230, v230, v90, v91
	v_max3_f32 v230, v230, v92, v93
	ds_read_b64_tr_b16 v[224:225], v174 offset:0x6200
	ds_read_b64_tr_b16 v[226:227], v174 offset:0x6a00
	s_waitcnt lgkmcnt(6)
	v_mfma_f32_32x32x16_bf16 v[48:63], v[202:205], v[238:241], v[48:63]
	v_max3_f32 v230, v230, v94, v95
	v_max3_f32 v230, v230, v64, v65
	v_max3_f32 v230, v230, v66, v67
	ds_read_b64_tr_b16 v[238:239], v174 offset:0x7200
	ds_read_b64_tr_b16 v[240:241], v174 offset:0x7a00
	s_waitcnt lgkmcnt(6)
	v_mfma_f32_32x32x16_bf16 v[32:47], v[146:149], v[208:211], v[32:47]
	v_max3_f32 v230, v230, v68, v69
	v_max3_f32 v230, v230, v70, v71
	v_max3_f32 v230, v230, v72, v73
	ds_read_b64_tr_b16 v[208:209], v174 offset:0x4400
	ds_read_b64_tr_b16 v[210:211], v174 offset:0x4c00
	s_waitcnt lgkmcnt(6)
	v_mfma_f32_32x32x16_bf16 v[32:47], v[194:197], v[220:223], v[32:47]
	v_max3_f32 v230, v230, v74, v75
	v_max3_f32 v230, v230, v76, v77
	v_max3_f32 v230, v230, v78, v79
	ds_read_b64_tr_b16 v[220:221], v174 offset:0x5400
	ds_read_b64_tr_b16 v[222:223], v174 offset:0x5c00
	s_waitcnt lgkmcnt(6)
	v_mfma_f32_32x32x16_bf16 v[32:47], v[198:201], v[224:227], v[32:47]
	v_mov_b32_e32 v231, v230
	s_nop 1
	v_permlane32_swap_b32_e32 v230, v231
	ds_read_b64_tr_b16 v[224:225], v174 offset:0x6400
	ds_read_b64_tr_b16 v[226:227], v174 offset:0x6c00
	s_waitcnt lgkmcnt(6)
	v_mfma_f32_32x32x16_bf16 v[32:47], v[202:205], v[238:241], v[32:47]
	v_max_f32_e32 v231, v231, v231
	v_max_f32_e32 v230, v230, v230
	v_max_f32_e32 v230, v230, v231
	ds_read_b64_tr_b16 v[238:239], v174 offset:0x7400
	ds_read_b64_tr_b16 v[240:241], v174 offset:0x7c00
	s_waitcnt lgkmcnt(6)
	v_mfma_f32_32x32x16_bf16 v[16:31], v[146:149], v[208:211], v[16:31]
	v_sub_f32_e32 v231, v230, v187
	v_mul_f32_e32 v231, 0x3db504f3, v231
	s_mov_b32 s6, 0x41000000
	ds_read_b64_tr_b16 v[208:209], v174 offset:0x4600
	ds_read_b64_tr_b16 v[210:211], v174 offset:0x4e00
	s_waitcnt lgkmcnt(6)
	v_mfma_f32_32x32x16_bf16 v[16:31], v[194:197], v[220:223], v[16:31]
	v_cmp_ge_f32_e32 vcc, s6, v231
	v_max_f32_e32 v231, v187, v187
	v_max_f32_e32 v231, v231, v230
	ds_read_b64_tr_b16 v[220:221], v174 offset:0x5600
	ds_read_b64_tr_b16 v[222:223], v174 offset:0x5e00
	s_waitcnt lgkmcnt(6)
	v_mfma_f32_32x32x16_bf16 v[16:31], v[198:201], v[224:227], v[16:31]
	v_sub_f32_e32 v230, v187, v231
	v_mul_f32_e32 v230, 0x3e0293ee, v230
	v_exp_f32_e32 v230, v230
	ds_read_b64_tr_b16 v[224:225], v174 offset:0x6600
	ds_read_b64_tr_b16 v[226:227], v174 offset:0x6e00
	s_waitcnt lgkmcnt(6)
	v_mfma_f32_32x32x16_bf16 v[16:31], v[202:205], v[238:241], v[16:31]
	ds_read_b64_tr_b16 v[238:239], v174 offset:0x7600
	ds_read_b64_tr_b16 v[240:241], v174 offset:0x7e00
	s_waitcnt lgkmcnt(6)
	v_mfma_f32_32x32x16_bf16 v[0:15], v[146:149], v[208:211], v[0:15]
	s_waitcnt lgkmcnt(4)
	v_mfma_f32_32x32x16_bf16 v[0:15], v[194:197], v[220:223], v[0:15]
	s_waitcnt lgkmcnt(2)
	v_mfma_f32_32x32x16_bf16 v[0:15], v[198:201], v[224:227], v[0:15]
	s_waitcnt lgkmcnt(0)
	v_mfma_f32_32x32x16_bf16 v[0:15], v[202:205], v[238:241], v[0:15]
	s_nop 0
	v_mov_b32_e32 v146, v230
	v_mov_b32_e32 v147, v231
	s_branch .Lpvj_1167b

.LBB0_1354:
	ds_read_b128 v[80:83], v193
	ds_read_b128 v[84:87], v193 offset:32
	ds_read_b128 v[64:67], v193 offset:128
	ds_read_b128 v[68:71], v193 offset:160
	ds_read_b128 v[88:91], v193 offset:64
	ds_read_b128 v[72:75], v193 offset:192
	ds_read_b128 v[92:95], v193 offset:96
	ds_read_b128 v[76:79], v193 offset:224
	ds_read_b128 v[130:133], v187 offset:49152
	s_waitcnt vmcnt(2)
	ds_read_b128 v[134:137], v187 offset:57344
	s_waitcnt vmcnt(1)
	v_exp_f32_e32 v138, v146
	v_add_f32_e32 v146, 0, v203
	v_add_f32_e32 v146, v204, v146
	s_waitcnt lgkmcnt(1)
	v_mfma_f32_32x32x16_bf16 v[80:95], v[130:133], v[126:129], v[80:95]
	v_add_f32_e32 v146, v205, v146
	v_add_f32_e32 v146, v207, v146
	v_add_f32_e32 v146, v208, v146
	v_add_f32_e32 v146, v210, v146
	v_add_f32_e32 v146, v206, v146
	v_add_f32_e32 v146, v209, v146
	v_add_f32_e32 v146, v173, v146
	s_waitcnt lgkmcnt(0)
	v_mfma_f32_32x32x16_bf16 v[64:79], v[134:137], v[126:129], v[64:79]
	ds_read_b128 v[130:133], v188 offset:49152
	ds_read_b128 v[134:137], v188 offset:57344
	v_add_f32_e32 v146, v175, v146
	v_add_f32_e32 v146, v198, v146
	v_add_f32_e32 v146, v201, v146
	v_add_f32_e32 v146, v174, v146
	v_add_f32_e32 v146, v199, v146
	v_add_f32_e32 v146, v200, v146
	s_waitcnt lgkmcnt(1)
	v_mfma_f32_32x32x16_bf16 v[80:95], v[130:133], v[122:125], v[80:95]
	v_add_f32_e32 v146, v202, v146
	v_exp_f32_e32 v139, v147
	v_exp_f32_e32 v140, v160
	v_exp_f32_e32 v141, v161
	s_waitcnt vmcnt(0)
	v_exp_f32_e32 v142, v154
	v_exp_f32_e32 v143, v155
	v_exp_f32_e32 v144, v148
	s_waitcnt lgkmcnt(0)
	v_mfma_f32_32x32x16_bf16 v[64:79], v[134:137], v[122:125], v[64:79]
	ds_read_b128 v[130:133], v186 offset:49152
	ds_read_b128 v[134:137], v186 offset:57344
	v_exp_f32_e32 v145, v149
	v_cvt_pk_bf16_f32 v147, v205, v207
	v_cvt_pk_bf16_f32 v148, v208, v210
	v_cvt_pk_bf16_f32 v149, v206, v209
	v_cvt_pk_bf16_f32 v160, v142, v143
	v_cvt_pk_bf16_f32 v161, v144, v145
	s_waitcnt lgkmcnt(1)
	v_mfma_f32_32x32x16_bf16 v[80:95], v[130:133], v[118:121], v[80:95]
	v_permlane32_swap_b32_e32 v147, v149
	s_waitcnt lgkmcnt(0)
	v_mfma_f32_32x32x16_bf16 v[64:79], v[134:137], v[118:121], v[64:79]
	ds_read_b128 v[130:133], v167 offset:49152
	ds_read_b128 v[134:137], v167 offset:57344
	s_waitcnt lgkmcnt(1)
	v_mfma_f32_32x32x16_bf16 v[80:95], v[130:133], v[114:117], v[80:95]
	s_waitcnt lgkmcnt(0)
	v_mfma_f32_32x32x16_bf16 v[64:79], v[134:137], v[114:117], v[64:79]
	ds_read_b128 v[130:133], v187 offset:49280
	ds_read_b128 v[134:137], v187 offset:57472
	s_waitcnt lgkmcnt(1)
	v_mfma_f32_32x32x16_bf16 v[80:95], v[130:133], v[110:113], v[80:95]
	s_waitcnt lgkmcnt(0)
	v_mfma_f32_32x32x16_bf16 v[64:79], v[134:137], v[110:113], v[64:79]
	ds_read_b128 v[130:133], v188 offset:49280
	ds_read_b128 v[134:137], v188 offset:57472
	s_waitcnt lgkmcnt(1)
	v_mfma_f32_32x32x16_bf16 v[80:95], v[130:133], v[106:109], v[80:95]
	s_waitcnt lgkmcnt(0)
	v_mfma_f32_32x32x16_bf16 v[64:79], v[134:137], v[106:109], v[64:79]
	ds_read_b128 v[130:133], v186 offset:49280
	ds_read_b128 v[134:137], v186 offset:57472
	s_waitcnt lgkmcnt(1)
	v_mfma_f32_32x32x16_bf16 v[80:95], v[130:133], v[102:105], v[80:95]
	s_waitcnt lgkmcnt(0)
	v_mfma_f32_32x32x16_bf16 v[64:79], v[134:137], v[102:105], v[64:79]
	ds_read_b128 v[130:133], v167 offset:49280
	ds_read_b128 v[134:137], v167 offset:57472
	s_waitcnt lgkmcnt(1)
	v_mfma_f32_32x32x16_bf16 v[80:95], v[130:133], v[98:101], v[80:95]
	v_exp_f32_e32 v130, v158
	v_exp_f32_e32 v131, v159
	v_exp_f32_e32 v132, v156
	v_exp_f32_e32 v133, v157
	v_add_f32_e32 v146, v130, v146
	v_add_f32_e32 v146, v131, v146
	v_add_f32_e32 v146, v132, v146
	s_waitcnt lgkmcnt(0)
	v_mfma_f32_32x32x16_bf16 v[64:79], v[134:137], v[98:101], v[64:79]
	v_exp_f32_e32 v134, v152
	v_exp_f32_e32 v135, v153
	v_exp_f32_e32 v136, v150
	v_exp_f32_e32 v137, v151
	v_add_f32_e32 v146, v133, v146
	v_add_f32_e32 v146, v134, v146
	v_add_f32_e32 v146, v135, v146
	v_add_f32_e32 v146, v136, v146
	v_add_f32_e32 v146, v137, v146
	v_add_f32_e32 v146, v138, v146
	v_add_f32_e32 v146, v139, v146
	v_add_f32_e32 v146, v140, v146
	v_add_f32_e32 v146, v141, v146
	v_add_f32_e32 v146, v142, v146
	v_add_f32_e32 v146, v143, v146
	v_add_f32_e32 v146, v144, v146
	v_add_f32_e32 v195, v145, v146
	v_mov_b32_e32 v196, v195
	s_nop 1
	v_permlane32_swap_b32_e32 v195, v196
	v_cvt_pk_bf16_f32 v146, v203, v204
	v_cvt_pk_bf16_f32 v150, v173, v175
	v_cvt_pk_bf16_f32 v151, v198, v201
	v_cvt_pk_bf16_f32 v152, v174, v199
	v_cvt_pk_bf16_f32 v153, v200, v202
	v_cvt_pk_bf16_f32 v154, v130, v131
	v_cvt_pk_bf16_f32 v155, v132, v133
	v_cvt_pk_bf16_f32 v156, v134, v135
	v_cvt_pk_bf16_f32 v157, v136, v137
	v_cvt_pk_bf16_f32 v158, v138, v139
	v_cvt_pk_bf16_f32 v159, v140, v141
	v_permlane32_swap_b32_e32 v146, v148
	v_permlane32_swap_b32_e32 v150, v152
	v_permlane32_swap_b32_e32 v151, v153
	v_permlane32_swap_b32_e32 v154, v156
	v_permlane32_swap_b32_e32 v155, v157
	v_permlane32_swap_b32_e32 v158, v160
	v_permlane32_swap_b32_e32 v159, v161
	v_lshl_add_u64 v[174:175], v[168:169], 0, v[96:97]
	s_mov_b32 s6, 0x15c40000
	v_add_co_u32_e32 v130, vcc, s6, v174
	s_mov_b32 s6, 0x15c50000
	s_nop 0
	v_addc_co_u32_e32 v131, vcc, 0, v175, vcc
	v_add_co_u32_e32 v134, vcc, s6, v174
	v_lshl_add_u64 v[172:173], v[170:171], 0, v[96:97]
	s_nop 0
	v_addc_co_u32_e32 v135, vcc, 0, v175, vcc
	s_mov_b32 s6, 0x14b40000
	v_add_co_u32_e32 v138, vcc, s6, v172
	s_mov_b32 s6, 0x14b50000
	s_nop 0
	v_addc_co_u32_e32 v139, vcc, 0, v173, vcc
	v_add_co_u32_e32 v142, vcc, s6, v172
	global_load_dwordx4 v[130:133], v[130:131], off
	s_nop 0
	global_load_dwordx4 v[134:137], v[134:135], off
	v_addc_co_u32_e32 v143, vcc, 0, v173, vcc
	global_load_dwordx4 v[138:141], v[138:139], off
	s_nop 0
	global_load_dwordx4 v[142:145], v[142:143], off
	s_sub_i32 s6, s92, 64
	s_cmp_le_i32 s6, s41
	s_cbranch_scc0 .Lpvm_1354a
	ds_read_b64_tr_b16 v[198:199], v180 offset:0
	ds_read_b64_tr_b16 v[200:201], v180 offset:0x800
	ds_read_b64_tr_b16 v[202:203], v180 offset:0x1000
	ds_read_b64_tr_b16 v[204:205], v180 offset:0x1800
	ds_read_b64_tr_b16 v[206:207], v180 offset:0x2000
	ds_read_b64_tr_b16 v[208:209], v180 offset:0x2800
	ds_read_b64_tr_b16 v[210:211], v180 offset:0x3000
	ds_read_b64_tr_b16 v[212:213], v180 offset:0x3800
	s_nop 0
	s_waitcnt lgkmcnt(6)
	v_mfma_f32_32x32x16_bf16 v[48:63], v[146:149], v[198:201], v[48:63]
	v_max_f32_e32 v230, v81, v81
	v_max_f32_e32 v231, v80, v80
	v_max_f32_e32 v230, v231, v230
	ds_read_b64_tr_b16 v[198:199], v180 offset:0x200
	ds_read_b64_tr_b16 v[200:201], v180 offset:0xa00
	s_waitcnt lgkmcnt(6)
	v_mfma_f32_32x32x16_bf16 v[48:63], v[150:153], v[202:205], v[48:63]
	v_max3_f32 v230, v230, v82, v83
	v_max3_f32 v230, v230, v84, v85
	v_max3_f32 v230, v230, v86, v87
	ds_read_b64_tr_b16 v[202:203], v180 offset:0x1200
	ds_read_b64_tr_b16 v[204:205], v180 offset:0x1a00
	s_waitcnt lgkmcnt(6)
	v_mfma_f32_32x32x16_bf16 v[48:63], v[154:157], v[206:209], v[48:63]
	v_max3_f32 v230, v230, v88, v89
	v_max3_f32 v230, v230, v90, v91
	v_max3_f32 v230, v230, v92, v93
	ds_read_b64_tr_b16 v[206:207], v180 offset:0x2200
	ds_read_b64_tr_b16 v[208:209], v180 offset:0x2a00
	s_waitcnt lgkmcnt(6)
	v_mfma_f32_32x32x16_bf16 v[48:63], v[158:161], v[210:213], v[48:63]
	v_max3_f32 v230, v230, v94, v95
	v_max3_f32 v230, v230, v64, v65
	v_max3_f32 v230, v230, v66, v67
	ds_read_b64_tr_b16 v[210:211], v180 offset:0x3200
	ds_read_b64_tr_b16 v[212:213], v180 offset:0x3a00
	s_waitcnt lgkmcnt(6)
	v_mfma_f32_32x32x16_bf16 v[32:47], v[146:149], v[198:201], v[32:47]
	v_max3_f32 v230, v230, v68, v69
	v_max3_f32 v230, v230, v70, v71
	v_max3_f32 v230, v230, v72, v73
	ds_read_b64_tr_b16 v[198:199], v180 offset:0x400
	ds_read_b64_tr_b16 v[200:201], v180 offset:0xc00
	s_waitcnt lgkmcnt(6)
	v_mfma_f32_32x32x16_bf16 v[32:47], v[150:153], v[202:205], v[32:47]
	v_max3_f32 v230, v230, v74, v75
	v_max3_f32 v230, v230, v76, v77
	v_max3_f32 v230, v230, v78, v79
	ds_read_b64_tr_b16 v[202:203], v180 offset:0x1400
	ds_read_b64_tr_b16 v[204:205], v180 offset:0x1c00
	s_waitcnt lgkmcnt(6)
	v_mfma_f32_32x32x16_bf16 v[32:47], v[154:157], v[206:209], v[32:47]
	v_mov_b32_e32 v231, v230
	s_nop 1
	v_permlane32_swap_b32_e32 v230, v231
	ds_read_b64_tr_b16 v[206:207], v180 offset:0x2400
	ds_read_b64_tr_b16 v[208:209], v180 offset:0x2c00
	s_waitcnt lgkmcnt(6)
	v_mfma_f32_32x32x16_bf16 v[32:47], v[158:161], v[210:213], v[32:47]
	v_max_f32_e32 v231, v231, v231
	v_max_f32_e32 v230, v230, v230
	v_max_f32_e32 v230, v230, v231
	ds_read_b64_tr_b16 v[210:211], v180 offset:0x3400
	ds_read_b64_tr_b16 v[212:213], v180 offset:0x3c00
	s_waitcnt lgkmcnt(6)
	v_mfma_f32_32x32x16_bf16 v[16:31], v[146:149], v[198:201], v[16:31]
	v_sub_f32_e32 v231, v230, v194
	v_mul_f32_e32 v231, 0x3db504f3, v231
	s_mov_b32 s6, 0x41000000
	ds_read_b64_tr_b16 v[198:199], v180 offset:0x600
	ds_read_b64_tr_b16 v[200:201], v180 offset:0xe00
	s_waitcnt lgkmcnt(6)
	v_mfma_f32_32x32x16_bf16 v[16:31], v[150:153], v[202:205], v[16:31]
	v_cmp_ge_f32_e32 vcc, s6, v231
	v_max_f32_e32 v231, v194, v194
	v_max_f32_e32 v230, v231, v230
	ds_read_b64_tr_b16 v[202:203], v180 offset:0x1600
	ds_read_b64_tr_b16 v[204:205], v180 offset:0x1e00
	s_waitcnt lgkmcnt(6)
	v_mfma_f32_32x32x16_bf16 v[16:31], v[154:157], v[206:209], v[16:31]
	v_sub_f32_e32 v231, v194, v230
	v_mul_f32_e32 v231, 0x3e0293ee, v231
	v_exp_f32_e32 v231, v231
	ds_read_b64_tr_b16 v[206:207], v180 offset:0x2600
	ds_read_b64_tr_b16 v[208:209], v180 offset:0x2e00
	s_waitcnt lgkmcnt(6)
	v_mfma_f32_32x32x16_bf16 v[16:31], v[158:161], v[210:213], v[16:31]
	ds_read_b64_tr_b16 v[210:211], v180 offset:0x3600
	ds_read_b64_tr_b16 v[212:213], v180 offset:0x3e00
	s_waitcnt lgkmcnt(6)
	v_mfma_f32_32x32x16_bf16 v[0:15], v[146:149], v[198:201], v[0:15]
	s_waitcnt lgkmcnt(4)
	v_mfma_f32_32x32x16_bf16 v[0:15], v[150:153], v[202:205], v[0:15]
	s_waitcnt lgkmcnt(2)
	v_mfma_f32_32x32x16_bf16 v[0:15], v[154:157], v[206:209], v[0:15]
	s_waitcnt lgkmcnt(0)
	v_mfma_f32_32x32x16_bf16 v[0:15], v[158:161], v[210:213], v[0:15]
	s_nop 0
	v_mov_b32_e32 v146, v230
	v_mov_b32_e32 v147, v231
	s_branch .Lpvj_1354a

.LBB0_1362:
	s_cmp_le_i32 s92, s41
	s_cbranch_scc0 .Lpvm_1354b
	ds_read_b64_tr_b16 v[172:173], v180 offset:0x4000
	ds_read_b64_tr_b16 v[174:175], v180 offset:0x4800
	ds_read_b64_tr_b16 v[198:199], v180 offset:0x5000
	ds_read_b64_tr_b16 v[200:201], v180 offset:0x5800
	ds_read_b64_tr_b16 v[202:203], v180 offset:0x6000
	ds_read_b64_tr_b16 v[204:205], v180 offset:0x6800
	ds_read_b64_tr_b16 v[206:207], v180 offset:0x7000
	ds_read_b64_tr_b16 v[208:209], v180 offset:0x7800
	s_nop 0
	s_waitcnt lgkmcnt(6)
	v_mfma_f32_32x32x16_bf16 v[48:63], v[146:149], v[172:175], v[48:63]
	v_max_f32_e32 v230, v81, v81
	v_max_f32_e32 v231, v80, v80
	ds_read_b64_tr_b16 v[172:173], v180 offset:0x4200
	ds_read_b64_tr_b16 v[174:175], v180 offset:0x4a00
	s_waitcnt lgkmcnt(6)
	v_mfma_f32_32x32x16_bf16 v[48:63], v[150:153], v[198:201], v[48:63]
	v_max_f32_e32 v230, v231, v230
	v_max3_f32 v230, v230, v82, v83
	ds_read_b64_tr_b16 v[198:199], v180 offset:0x5200
	ds_read_b64_tr_b16 v[200:201], v180 offset:0x5a00
	s_waitcnt lgkmcnt(6)
	v_mfma_f32_32x32x16_bf16 v[48:63], v[154:157], v[202:205], v[48:63]
	v_max3_f32 v230, v230, v84, v85
	v_max3_f32 v230, v230, v86, v87
	ds_read_b64_tr_b16 v[202:203], v180 offset:0x6200
	ds_read_b64_tr_b16 v[204:205], v180 offset:0x6a00
	s_waitcnt lgkmcnt(6)
	v_mfma_f32_32x32x16_bf16 v[48:63], v[158:161], v[206:209], v[48:63]
	v_max3_f32 v230, v230, v88, v89
	v_max3_f32 v230, v230, v90, v91
	ds_read_b64_tr_b16 v[206:207], v180 offset:0x7200
	ds_read_b64_tr_b16 v[208:209], v180 offset:0x7a00
	s_waitcnt lgkmcnt(6)
	v_mfma_f32_32x32x16_bf16 v[32:47], v[146:149], v[172:175], v[32:47]
	v_max3_f32 v230, v230, v92, v93
	v_max3_f32 v230, v230, v94, v95
	ds_read_b64_tr_b16 v[172:173], v180 offset:0x4400
	ds_read_b64_tr_b16 v[174:175], v180 offset:0x4c00
	s_waitcnt lgkmcnt(6)
	v_mfma_f32_32x32x16_bf16 v[32:47], v[150:153], v[198:201], v[32:47]
	v_max3_f32 v230, v230, v64, v65
	v_max3_f32 v230, v230, v66, v67
	ds_read_b64_tr_b16 v[198:199], v180 offset:0x5400
	ds_read_b64_tr_b16 v[200:201], v180 offset:0x5c00
	s_waitcnt lgkmcnt(6)
	v_mfma_f32_32x32x16_bf16 v[32:47], v[154:157], v[202:205], v[32:47]
	v_max3_f32 v230, v230, v68, v69
	v_max3_f32 v230, v230, v70, v71
	ds_read_b64_tr_b16 v[202:203], v180 offset:0x6400
	ds_read_b64_tr_b16 v[204:205], v180 offset:0x6c00
	s_waitcnt lgkmcnt(6)
	v_mfma_f32_32x32x16_bf16 v[32:47], v[158:161], v[206:209], v[32:47]
	v_max3_f32 v230, v230, v72, v73
	v_max3_f32 v230, v230, v74, v75
	ds_read_b64_tr_b16 v[206:207], v180 offset:0x7400
	ds_read_b64_tr_b16 v[208:209], v180 offset:0x7c00
	s_waitcnt lgkmcnt(6)
	v_mfma_f32_32x32x16_bf16 v[16:31], v[146:149], v[172:175], v[16:31]
	v_max3_f32 v230, v230, v76, v77
	v_max3_f32 v230, v230, v78, v79
	ds_read_b64_tr_b16 v[172:173], v180 offset:0x4600
	ds_read_b64_tr_b16 v[174:175], v180 offset:0x4e00
	s_waitcnt lgkmcnt(6)
	v_mfma_f32_32x32x16_bf16 v[16:31], v[150:153], v[198:201], v[16:31]
	v_mov_b32_e32 v231, v230
	s_nop 1
	ds_read_b64_tr_b16 v[198:199], v180 offset:0x5600
	ds_read_b64_tr_b16 v[200:201], v180 offset:0x5e00
	s_waitcnt lgkmcnt(6)
	v_mfma_f32_32x32x16_bf16 v[16:31], v[154:157], v[202:205], v[16:31]
	v_permlane32_swap_b32_e32 v230, v231
	v_max_f32_e32 v231, v231, v231
	ds_read_b64_tr_b16 v[202:203], v180 offset:0x6600
	ds_read_b64_tr_b16 v[204:205], v180 offset:0x6e00
	s_waitcnt lgkmcnt(6)
	v_mfma_f32_32x32x16_bf16 v[16:31], v[158:161], v[206:209], v[16:31]
	v_max_f32_e32 v230, v230, v230
	v_max_f32_e32 v230, v230, v231
	ds_read_b64_tr_b16 v[206:207], v180 offset:0x7600
	ds_read_b64_tr_b16 v[208:209], v180 offset:0x7e00
	s_waitcnt lgkmcnt(6)
	v_mfma_f32_32x32x16_bf16 v[0:15], v[146:149], v[172:175], v[0:15]
	v_sub_f32_e32 v231, v230, v194
	v_mul_f32_e32 v231, 0x3db504f3, v231
	s_waitcnt lgkmcnt(4)
	v_mfma_f32_32x32x16_bf16 v[0:15], v[150:153], v[198:201], v[0:15]
	s_mov_b32 s6, 0x41000000
	v_cmp_ge_f32_e32 vcc, s6, v231
	s_waitcnt lgkmcnt(2)
	v_mfma_f32_32x32x16_bf16 v[0:15], v[154:157], v[202:205], v[0:15]
	s_waitcnt lgkmcnt(0)
	v_mfma_f32_32x32x16_bf16 v[0:15], v[158:161], v[206:209], v[0:15]
	s_nop 0
	v_mov_b32_e32 v146, v230
	v_mov_b32_e32 v147, v231
	s_branch .Lpvj_1354b

.LBB0_1518:
	ds_read_b128 v[80:83], v200
	ds_read_b128 v[84:87], v200 offset:32
	ds_read_b128 v[64:67], v200 offset:128
	ds_read_b128 v[68:71], v200 offset:160
	ds_read_b128 v[88:91], v200 offset:64
	ds_read_b128 v[72:75], v200 offset:192
	ds_read_b128 v[92:95], v200 offset:96
	ds_read_b128 v[76:79], v200 offset:224
	ds_read_b128 v[208:211], v194 offset:49152
	ds_read_b128 v[220:223], v194 offset:57344
	v_add_f32_e32 v146, 0, v147
	v_add_f32_e32 v146, v148, v146
	v_add_f32_e32 v146, v149, v146
	s_waitcnt lgkmcnt(1)
	v_mfma_f32_32x32x16_bf16 v[80:95], v[208:211], v[126:129], v[80:95]
	v_add_f32_e32 v146, v160, v146
	v_add_f32_e32 v146, v161, v146
	v_add_f32_e32 v146, v207, v146
	v_add_f32_e32 v146, v159, v146
	v_add_f32_e32 v146, v206, v146
	v_add_f32_e32 v146, v151, v146
	v_add_f32_e32 v146, v153, v146
	s_waitcnt lgkmcnt(0)
	v_mfma_f32_32x32x16_bf16 v[64:79], v[220:223], v[126:129], v[64:79]
	ds_read_b128 v[208:211], v195 offset:49152
	ds_read_b128 v[220:223], v195 offset:57344
	v_add_f32_e32 v146, v154, v146
	v_add_f32_e32 v146, v155, v146
	v_exp_f32_e32 v144, v144
	v_add_f32_e32 v146, v152, v146
	v_exp_f32_e32 v145, v145
	v_add_f32_e32 v146, v156, v146
	s_waitcnt lgkmcnt(1)
	v_mfma_f32_32x32x16_bf16 v[80:95], v[208:211], v[122:125], v[80:95]
	v_exp_f32_e32 v142, v142
	v_add_f32_e32 v146, v157, v146
	v_exp_f32_e32 v143, v143
	v_add_f32_e32 v146, v158, v146
	v_exp_f32_e32 v140, v140
	v_add_f32_e32 v146, v144, v146
	v_exp_f32_e32 v141, v141
	s_waitcnt lgkmcnt(0)
	v_mfma_f32_32x32x16_bf16 v[64:79], v[220:223], v[122:125], v[64:79]
	ds_read_b128 v[208:211], v193 offset:49152
	ds_read_b128 v[220:223], v193 offset:57344
	v_add_f32_e32 v146, v145, v146
	v_exp_f32_e32 v138, v138
	v_add_f32_e32 v146, v142, v146
	v_exp_f32_e32 v139, v139
	v_add_f32_e32 v146, v143, v146
	v_exp_f32_e32 v136, v136
	s_waitcnt lgkmcnt(1)
	v_mfma_f32_32x32x16_bf16 v[80:95], v[208:211], v[118:121], v[80:95]
	v_add_f32_e32 v146, v140, v146
	v_exp_f32_e32 v137, v137
	v_add_f32_e32 v146, v141, v146
	v_exp_f32_e32 v134, v134
	v_add_f32_e32 v146, v138, v146
	v_exp_f32_e32 v135, v135
	v_add_f32_e32 v146, v139, v146
	s_waitcnt lgkmcnt(0)
	v_mfma_f32_32x32x16_bf16 v[64:79], v[220:223], v[118:121], v[64:79]
	ds_read_b128 v[208:211], v192 offset:49152
	ds_read_b128 v[220:223], v192 offset:57344
	v_exp_f32_e32 v132, v132
	v_add_f32_e32 v146, v136, v146
	v_exp_f32_e32 v133, v133
	v_add_f32_e32 v146, v137, v146
	v_exp_f32_e32 v130, v130
	v_add_f32_e32 v146, v134, v146
	s_waitcnt lgkmcnt(1)
	v_mfma_f32_32x32x16_bf16 v[80:95], v[208:211], v[114:117], v[80:95]
	v_exp_f32_e32 v131, v131
	v_add_f32_e32 v146, v135, v146
	v_add_f32_e32 v146, v132, v146
	v_add_f32_e32 v146, v133, v146
	v_add_f32_e32 v146, v130, v146
	v_add_f32_e32 v203, v131, v146
	v_mov_b32_e32 v204, v203
	s_waitcnt lgkmcnt(0)
	v_mfma_f32_32x32x16_bf16 v[64:79], v[220:223], v[114:117], v[64:79]
	ds_read_b128 v[208:211], v194 offset:49280
	ds_read_b128 v[220:223], v194 offset:57472
	v_permlane32_swap_b32_e32 v203, v204
	v_cvt_pk_bf16_f32 v146, v147, v148
	v_cvt_pk_bf16_f32 v147, v149, v160
	v_cvt_pk_bf16_f32 v148, v161, v207
	v_cvt_pk_bf16_f32 v149, v159, v206
	s_waitcnt lgkmcnt(1)
	v_mfma_f32_32x32x16_bf16 v[80:95], v[208:211], v[110:113], v[80:95]
	v_cvt_pk_bf16_f32 v206, v151, v153
	v_cvt_pk_bf16_f32 v207, v154, v155
	v_cvt_pk_bf16_f32 v153, v142, v143
	v_cvt_pk_bf16_f32 v154, v140, v141
	v_cvt_pk_bf16_f32 v155, v138, v139
	v_cvt_pk_bf16_f32 v159, v130, v131
	v_permlane32_swap_b32_e32 v146, v148
	s_waitcnt lgkmcnt(0)
	v_mfma_f32_32x32x16_bf16 v[64:79], v[220:223], v[110:113], v[64:79]
	ds_read_b128 v[208:211], v195 offset:49280
	ds_read_b128 v[220:223], v195 offset:57472
	v_permlane32_swap_b32_e32 v147, v149
	v_permlane32_swap_b32_e32 v153, v155
	s_waitcnt lgkmcnt(1)
	v_mfma_f32_32x32x16_bf16 v[80:95], v[208:211], v[106:109], v[80:95]
	s_waitcnt lgkmcnt(0)
	v_mfma_f32_32x32x16_bf16 v[64:79], v[220:223], v[106:109], v[64:79]
	ds_read_b128 v[208:211], v193 offset:49280
	ds_read_b128 v[220:223], v193 offset:57472
	s_waitcnt lgkmcnt(1)
	v_mfma_f32_32x32x16_bf16 v[80:95], v[208:211], v[102:105], v[80:95]
	s_waitcnt lgkmcnt(0)
	v_mfma_f32_32x32x16_bf16 v[64:79], v[220:223], v[102:105], v[64:79]
	ds_read_b128 v[208:211], v192 offset:49280
	ds_read_b128 v[220:223], v192 offset:57472
	s_waitcnt lgkmcnt(1)
	v_mfma_f32_32x32x16_bf16 v[80:95], v[208:211], v[98:101], v[80:95]
	v_cvt_pk_bf16_f32 v208, v152, v156
	v_cvt_pk_bf16_f32 v209, v157, v158
	v_cvt_pk_bf16_f32 v152, v144, v145
	v_cvt_pk_bf16_f32 v156, v136, v137
	v_cvt_pk_bf16_f32 v157, v134, v135
	v_cvt_pk_bf16_f32 v158, v132, v133
	v_permlane32_swap_b32_e32 v206, v208
	s_waitcnt lgkmcnt(0)
	v_mfma_f32_32x32x16_bf16 v[64:79], v[220:223], v[98:101], v[64:79]
	v_permlane32_swap_b32_e32 v207, v209
	v_permlane32_swap_b32_e32 v152, v154
	v_permlane32_swap_b32_e32 v156, v158
	v_permlane32_swap_b32_e32 v157, v159
	v_lshl_add_u64 v[130:131], v[170:171], 0, v[96:97]
	v_lshl_add_u64 v[134:135], v[166:167], 0, v[96:97]
	v_lshl_add_u64 v[138:139], v[172:173], 0, v[96:97]
	v_lshl_add_u64 v[142:143], v[168:169], 0, v[96:97]
	global_load_dwordx4 v[130:133], v[130:131], off
	s_nop 0
	global_load_dwordx4 v[134:137], v[134:135], off
	s_nop 0
	global_load_dwordx4 v[138:141], v[138:139], off
	s_nop 0
	global_load_dwordx4 v[142:145], v[142:143], off
	s_sub_i32 s6, s74, 64
	s_cmp_le_i32 s6, s3
	s_cbranch_scc0 .Lpvm_1518a
	ds_read_b64_tr_b16 v[210:211], v188 offset:0
	ds_read_b64_tr_b16 v[212:213], v188 offset:0x800
	ds_read_b64_tr_b16 v[220:221], v188 offset:0x1000
	ds_read_b64_tr_b16 v[222:223], v188 offset:0x1800
	ds_read_b64_tr_b16 v[224:225], v188 offset:0x2000
	ds_read_b64_tr_b16 v[226:227], v188 offset:0x2800
	ds_read_b64_tr_b16 v[238:239], v188 offset:0x3000
	ds_read_b64_tr_b16 v[240:241], v188 offset:0x3800
	s_nop 0
	s_waitcnt lgkmcnt(6)
	v_mfma_f32_32x32x16_bf16 v[0:15], v[146:149], v[210:213], v[0:15]
	v_max_f32_e32 v230, v81, v81
	v_max_f32_e32 v231, v80, v80
	v_max_f32_e32 v230, v231, v230
	ds_read_b64_tr_b16 v[210:211], v188 offset:0x200
	ds_read_b64_tr_b16 v[212:213], v188 offset:0xa00
	s_waitcnt lgkmcnt(6)
	v_mfma_f32_32x32x16_bf16 v[0:15], v[206:209], v[220:223], v[0:15]
	v_max3_f32 v230, v230, v82, v83
	v_max3_f32 v230, v230, v84, v85
	v_max3_f32 v230, v230, v86, v87
	ds_read_b64_tr_b16 v[220:221], v188 offset:0x1200
	ds_read_b64_tr_b16 v[222:223], v188 offset:0x1a00
	s_waitcnt lgkmcnt(6)
	v_mfma_f32_32x32x16_bf16 v[0:15], v[152:155], v[224:227], v[0:15]
	v_max3_f32 v230, v230, v88, v89
	v_max3_f32 v230, v230, v90, v91
	v_max3_f32 v230, v230, v92, v93
	ds_read_b64_tr_b16 v[224:225], v188 offset:0x2200
	ds_read_b64_tr_b16 v[226:227], v188 offset:0x2a00
	s_waitcnt lgkmcnt(6)
	v_mfma_f32_32x32x16_bf16 v[0:15], v[156:159], v[238:241], v[0:15]
	v_max3_f32 v230, v230, v94, v95
	v_max3_f32 v230, v230, v64, v65
	v_max3_f32 v230, v230, v66, v67
	ds_read_b64_tr_b16 v[238:239], v188 offset:0x3200
	ds_read_b64_tr_b16 v[240:241], v188 offset:0x3a00
	s_waitcnt lgkmcnt(6)
	v_mfma_f32_32x32x16_bf16 v[48:63], v[146:149], v[210:213], v[48:63]
	v_max3_f32 v230, v230, v68, v69
	v_max3_f32 v230, v230, v70, v71
	v_max3_f32 v230, v230, v72, v73
	ds_read_b64_tr_b16 v[210:211], v188 offset:0x400
	ds_read_b64_tr_b16 v[212:213], v188 offset:0xc00
	s_waitcnt lgkmcnt(6)
	v_mfma_f32_32x32x16_bf16 v[48:63], v[206:209], v[220:223], v[48:63]
	v_max3_f32 v230, v230, v74, v75
	v_max3_f32 v230, v230, v76, v77
	v_max3_f32 v230, v230, v78, v79
	ds_read_b64_tr_b16 v[220:221], v188 offset:0x1400
	ds_read_b64_tr_b16 v[222:223], v188 offset:0x1c00
	s_waitcnt lgkmcnt(6)
	v_mfma_f32_32x32x16_bf16 v[48:63], v[152:155], v[224:227], v[48:63]
	v_mov_b32_e32 v231, v230
	s_nop 1
	v_permlane32_swap_b32_e32 v230, v231
	ds_read_b64_tr_b16 v[224:225], v188 offset:0x2400
	ds_read_b64_tr_b16 v[226:227], v188 offset:0x2c00
	s_waitcnt lgkmcnt(6)
	v_mfma_f32_32x32x16_bf16 v[48:63], v[156:159], v[238:241], v[48:63]
	v_max_f32_e32 v231, v231, v231
	v_max_f32_e32 v230, v230, v230
	v_max_f32_e32 v230, v230, v231
	ds_read_b64_tr_b16 v[238:239], v188 offset:0x3400
	ds_read_b64_tr_b16 v[240:241], v188 offset:0x3c00
	s_waitcnt lgkmcnt(6)
	v_mfma_f32_32x32x16_bf16 v[32:47], v[146:149], v[210:213], v[32:47]
	v_sub_f32_e32 v231, v230, v150
	v_mul_f32_e32 v231, 0x3db504f3, v231
	s_mov_b32 s6, 0x41000000
	ds_read_b64_tr_b16 v[210:211], v188 offset:0x600
	ds_read_b64_tr_b16 v[212:213], v188 offset:0xe00
	s_waitcnt lgkmcnt(6)
	v_mfma_f32_32x32x16_bf16 v[32:47], v[206:209], v[220:223], v[32:47]
	v_cmp_ge_f32_e32 vcc, s6, v231
	v_max_f32_e32 v231, v150, v150
	v_max_f32_e32 v230, v231, v230
	ds_read_b64_tr_b16 v[220:221], v188 offset:0x1600
	ds_read_b64_tr_b16 v[222:223], v188 offset:0x1e00
	s_waitcnt lgkmcnt(6)
	v_mfma_f32_32x32x16_bf16 v[32:47], v[152:155], v[224:227], v[32:47]
	v_sub_f32_e32 v231, v150, v230
	v_mul_f32_e32 v231, 0x3e0293ee, v231
	v_exp_f32_e32 v231, v231
	ds_read_b64_tr_b16 v[224:225], v188 offset:0x2600
	ds_read_b64_tr_b16 v[226:227], v188 offset:0x2e00
	s_waitcnt lgkmcnt(6)
	v_mfma_f32_32x32x16_bf16 v[32:47], v[156:159], v[238:241], v[32:47]
	ds_read_b64_tr_b16 v[238:239], v188 offset:0x3600
	ds_read_b64_tr_b16 v[240:241], v188 offset:0x3e00
	s_waitcnt lgkmcnt(6)
	v_mfma_f32_32x32x16_bf16 v[16:31], v[146:149], v[210:213], v[16:31]
	s_waitcnt lgkmcnt(4)
	v_mfma_f32_32x32x16_bf16 v[16:31], v[206:209], v[220:223], v[16:31]
	s_waitcnt lgkmcnt(2)
	v_mfma_f32_32x32x16_bf16 v[16:31], v[152:155], v[224:227], v[16:31]
	s_waitcnt lgkmcnt(0)
	v_mfma_f32_32x32x16_bf16 v[16:31], v[156:159], v[238:241], v[16:31]
	s_nop 0
	v_mov_b32_e32 v146, v230
	v_mov_b32_e32 v147, v231
	s_branch .Lpvj_1518a

.LBB0_1526:
	s_cmp_le_i32 s74, s3
	s_cbranch_scc0 .Lpvm_1518b
	ds_read_b64_tr_b16 v[210:211], v188 offset:0x4000
	ds_read_b64_tr_b16 v[212:213], v188 offset:0x4800
	ds_read_b64_tr_b16 v[220:221], v188 offset:0x5000
	ds_read_b64_tr_b16 v[222:223], v188 offset:0x5800
	ds_read_b64_tr_b16 v[224:225], v188 offset:0x6000
	ds_read_b64_tr_b16 v[226:227], v188 offset:0x6800
	ds_read_b64_tr_b16 v[238:239], v188 offset:0x7000
	ds_read_b64_tr_b16 v[240:241], v188 offset:0x7800
	s_nop 0
	s_waitcnt lgkmcnt(6)
	v_mfma_f32_32x32x16_bf16 v[0:15], v[146:149], v[210:213], v[0:15]
	v_max_f32_e32 v230, v81, v81
	v_max_f32_e32 v231, v80, v80
	ds_read_b64_tr_b16 v[210:211], v188 offset:0x4200
	ds_read_b64_tr_b16 v[212:213], v188 offset:0x4a00
	s_waitcnt lgkmcnt(6)
	v_mfma_f32_32x32x16_bf16 v[0:15], v[150:153], v[220:223], v[0:15]
	v_max_f32_e32 v230, v231, v230
	v_max3_f32 v230, v230, v82, v83
	ds_read_b64_tr_b16 v[220:221], v188 offset:0x5200
	ds_read_b64_tr_b16 v[222:223], v188 offset:0x5a00
	s_waitcnt lgkmcnt(6)
	v_mfma_f32_32x32x16_bf16 v[0:15], v[154:157], v[224:227], v[0:15]
	v_max3_f32 v230, v230, v84, v85
	v_max3_f32 v230, v230, v86, v87
	ds_read_b64_tr_b16 v[224:225], v188 offset:0x6200
	ds_read_b64_tr_b16 v[226:227], v188 offset:0x6a00
	s_waitcnt lgkmcnt(6)
	v_mfma_f32_32x32x16_bf16 v[0:15], v[158:161], v[238:241], v[0:15]
	v_max3_f32 v230, v230, v88, v89
	v_max3_f32 v230, v230, v90, v91
	ds_read_b64_tr_b16 v[238:239], v188 offset:0x7200
	ds_read_b64_tr_b16 v[240:241], v188 offset:0x7a00
	s_waitcnt lgkmcnt(6)
	v_mfma_f32_32x32x16_bf16 v[48:63], v[146:149], v[210:213], v[48:63]
	v_max3_f32 v230, v230, v92, v93
	v_max3_f32 v230, v230, v94, v95
	ds_read_b64_tr_b16 v[210:211], v188 offset:0x4400
	ds_read_b64_tr_b16 v[212:213], v188 offset:0x4c00
	s_waitcnt lgkmcnt(6)
	v_mfma_f32_32x32x16_bf16 v[48:63], v[150:153], v[220:223], v[48:63]
	v_max3_f32 v230, v230, v64, v65
	v_max3_f32 v230, v230, v66, v67
	ds_read_b64_tr_b16 v[220:221], v188 offset:0x5400
	ds_read_b64_tr_b16 v[222:223], v188 offset:0x5c00
	s_waitcnt lgkmcnt(6)
	v_mfma_f32_32x32x16_bf16 v[48:63], v[154:157], v[224:227], v[48:63]
	v_max3_f32 v230, v230, v68, v69
	v_max3_f32 v230, v230, v70, v71
	ds_read_b64_tr_b16 v[224:225], v188 offset:0x6400
	ds_read_b64_tr_b16 v[226:227], v188 offset:0x6c00
	s_waitcnt lgkmcnt(6)
	v_mfma_f32_32x32x16_bf16 v[48:63], v[158:161], v[238:241], v[48:63]
	v_max3_f32 v230, v230, v72, v73
	v_max3_f32 v230, v230, v74, v75
	ds_read_b64_tr_b16 v[238:239], v188 offset:0x7400
	ds_read_b64_tr_b16 v[240:241], v188 offset:0x7c00
	s_waitcnt lgkmcnt(6)
	v_mfma_f32_32x32x16_bf16 v[32:47], v[146:149], v[210:213], v[32:47]
	v_max3_f32 v230, v230, v76, v77
	v_max3_f32 v230, v230, v78, v79
	ds_read_b64_tr_b16 v[210:211], v188 offset:0x4600
	ds_read_b64_tr_b16 v[212:213], v188 offset:0x4e00
	s_waitcnt lgkmcnt(6)
	v_mfma_f32_32x32x16_bf16 v[32:47], v[150:153], v[220:223], v[32:47]
	v_mov_b32_e32 v231, v230
	s_nop 1
	ds_read_b64_tr_b16 v[220:221], v188 offset:0x5600
	ds_read_b64_tr_b16 v[222:223], v188 offset:0x5e00
	s_waitcnt lgkmcnt(6)
	v_mfma_f32_32x32x16_bf16 v[32:47], v[154:157], v[224:227], v[32:47]
	v_permlane32_swap_b32_e32 v230, v231
	v_max_f32_e32 v231, v231, v231
	ds_read_b64_tr_b16 v[224:225], v188 offset:0x6600
	ds_read_b64_tr_b16 v[226:227], v188 offset:0x6e00
	s_waitcnt lgkmcnt(6)
	v_mfma_f32_32x32x16_bf16 v[32:47], v[158:161], v[238:241], v[32:47]
	v_max_f32_e32 v230, v230, v230
	v_max_f32_e32 v230, v230, v231
	ds_read_b64_tr_b16 v[238:239], v188 offset:0x7600
	ds_read_b64_tr_b16 v[240:241], v188 offset:0x7e00
	s_waitcnt lgkmcnt(6)
	v_mfma_f32_32x32x16_bf16 v[16:31], v[146:149], v[210:213], v[16:31]
	v_sub_f32_e32 v231, v230, v206
	v_mul_f32_e32 v231, 0x3db504f3, v231
	s_waitcnt lgkmcnt(4)
	v_mfma_f32_32x32x16_bf16 v[16:31], v[150:153], v[220:223], v[16:31]
	s_mov_b32 s6, 0x41000000
	v_cmp_ge_f32_e32 vcc, s6, v231
	s_waitcnt lgkmcnt(2)
	v_mfma_f32_32x32x16_bf16 v[16:31], v[154:157], v[224:227], v[16:31]
	s_waitcnt lgkmcnt(0)
	v_mfma_f32_32x32x16_bf16 v[16:31], v[158:161], v[238:241], v[16:31]
	s_nop 0
	v_mov_b32_e32 v146, v230
	v_mov_b32_e32 v147, v231
	s_branch .Lpvj_1518b
